# in1 tiles additionally rotated per round so each block gets one q, k, v and g column tile instead of four of the same type
# baseline (speedup 1.0000x reference)
; DI int sched_tile(const Sched& sc, int round, int MT, int NT, int& mt, int& nt) {
;   const int total = MT * NT;
;   const int per = (total + sc.nx - 1) / sc.nx;
;   const int off = round * sc.minloc;
;   if (off >= per) return 2;
;   if (sc.rank >= sc.minloc) return 1;
;   int L = off + sc.rank;
;   if (L >= per) return 1;
;   L += sc.xs * per;
;   if (L >= total) return 1;
;   for (int c0 = 0; c0 < NT; c0 += 8) {
;     const int w = NT - c0 < 8 ? NT - c0 : 8;
;     const int cnt = MT * w;
;     if (L < cnt) { mt = L / w; nt = c0 + L - mt * w; return 0; }
.LBB0_756:
	s_mul_i32 s4, s42, s90
	s_cmp_ge_i32 s4, s33
	s_cselect_b64 s[6:7], -1, 0
	s_and_b64 s[20:21], s[6:7], exec
	s_cselect_b32 s5, 2, 1
	s_or_b64 s[6:7], s[6:7], s[94:95]
	s_and_b64 vcc, exec, s[6:7]
	v_mov_b32_e32 v0, s5
	s_mov_b32 s52, 0
	s_mov_b32 s20, 0
	s_cbranch_vccnz .LBB0_764
	s_add_i32 s4, s4, s92
	s_cmp_ge_i32 s4, s33
	s_cbranch_scc1 .LBB0_762
	s_add_i32 s22, s41, s4
	s_cmp_lg_u32 s33, 0xe0
	s_cbranch_scc1 .Lin1_noremap
	s_lshr_b32 s22, s41, 5
	s_mul_i32 s22, s22, 37
	s_lshr_b32 s22, s22, 8
	s_cmp_lt_u32 s4, 0x80
	s_cbranch_scc0 .Lin1_g2
	s_lshl_b32 s22, s22, 7
	s_cmp_lg_u32 s90, 32
	s_cbranch_scc1 .Lin1_norot
	s_lshr_b32 s23, s4, 5
	s_lshl_b32 s23, s23, 1
	s_add_i32 s23, s23, s4
	s_and_b32 s23, s23, 31
	s_add_i32 s22, s22, s23
	s_andn2_b32 s23, s4, 31
	s_add_i32 s22, s22, s23
	s_branch .Lin1_noremap
.Lin1_norot:
	s_add_i32 s22, s22, s4
	s_branch .Lin1_noremap
